# interleaved MFMA/ds_read/global_load/ds_write K-loop schedule also applied to the half-height GEMM0 tile loop and the GEMM1 out-proj loop
# speedup vs baseline: 1.0656x; 1.0113x over previous
.LBB0_374:
.Lgq_c:
	ds_read_b128 v[114:117], v188 offset:16384
	ds_read_b128 v[118:121], v188 offset:16896
	ds_read_b128 v[156:159], v188 offset:20480
	ds_read_b128 v[160:163], v188 offset:20992
	ds_read_b128 v[122:125], v112
	ds_read_b128 v[126:129], v112 offset:2048
	v_lshl_add_u64 v[62:63], v[98:99], 0, s[0:1]
	global_load_dwordx4 v[62:65], v[62:63], off offset:256
	s_add_u32 s6, s0, 0x11000
	s_addc_u32 s7, s1, 0
	v_lshl_add_u64 v[70:71], v[98:99], 0, s[6:7]
	global_load_dwordx4 v[70:73], v[70:71], off offset:256
	s_waitcnt lgkmcnt(1)
	v_mfma_f32_16x16x32_bf16 v[66:69], v[114:117], v[122:125], v[66:69]
	v_mfma_f32_16x16x32_bf16 v[58:61], v[118:121], v[122:125], v[58:61]
	s_add_u32 vcc_lo, s0, 0x22000
	s_addc_u32 vcc_hi, s1, 0
	v_lshl_add_u64 v[74:75], v[98:99], 0, vcc
	global_load_dwordx4 v[74:77], v[74:75], off offset:256
	v_mfma_f32_16x16x32_bf16 v[54:57], v[156:159], v[122:125], v[54:57]
	v_mfma_f32_16x16x32_bf16 v[50:53], v[160:163], v[122:125], v[50:53]
	s_waitcnt lgkmcnt(0)
	v_mfma_f32_16x16x32_bf16 v[46:49], v[114:117], v[126:129], v[46:49]
	ds_read_b128 v[180:183], v112 offset:4096
	ds_read_b128 v[184:187], v112 offset:6144
	v_mfma_f32_16x16x32_bf16 v[42:45], v[118:121], v[126:129], v[42:45]
	v_mfma_f32_16x16x32_bf16 v[38:41], v[156:159], v[126:129], v[38:41]
	s_add_u32 s6, s0, 0x33000
	s_addc_u32 s7, s1, 0
	v_lshl_add_u64 v[78:79], v[98:99], 0, s[6:7]
	global_load_dwordx4 v[78:81], v[78:79], off offset:256
	v_mfma_f32_16x16x32_bf16 v[34:37], v[160:163], v[126:129], v[34:37]
	s_waitcnt lgkmcnt(1)
	v_mfma_f32_16x16x32_bf16 v[30:33], v[114:117], v[180:183], v[30:33]
	ds_read_b128 v[164:167], v189 offset:16384
	ds_read_b128 v[168:171], v189 offset:16896
	v_mfma_f32_16x16x32_bf16 v[26:29], v[118:121], v[180:183], v[26:29]
	v_lshl_add_u64 v[82:83], v[100:101], 0, s[0:1]
	global_load_dwordx4 v[82:85], v[82:83], off offset:256
	v_mfma_f32_16x16x32_bf16 v[22:25], v[156:159], v[180:183], v[22:25]
	ds_read_b128 v[172:175], v189 offset:20480
	ds_read_b128 v[176:179], v189 offset:20992
	v_mfma_f32_16x16x32_bf16 v[18:21], v[160:163], v[180:183], v[18:21]
	s_waitcnt lgkmcnt(4)
	v_mfma_f32_16x16x32_bf16 v[14:17], v[114:117], v[184:187], v[14:17]
	ds_read_b128 v[122:125], v113
	ds_read_b128 v[126:129], v113 offset:2048
	v_mfma_f32_16x16x32_bf16 v[10:13], v[118:121], v[184:187], v[10:13]
	v_mfma_f32_16x16x32_bf16 v[6:9], v[156:159], v[184:187], v[6:9]
	s_add_u32 vcc_lo, s0, 0x11000
	s_addc_u32 vcc_hi, s1, 0
	v_lshl_add_u64 v[86:87], v[100:101], 0, vcc
	global_load_dwordx4 v[86:89], v[86:87], off offset:256
	v_mfma_f32_16x16x32_bf16 v[2:5], v[160:163], v[184:187], v[2:5]
	s_waitcnt lgkmcnt(1)
	v_mfma_f32_16x16x32_bf16 v[66:69], v[164:167], v[122:125], v[66:69]
	v_mfma_f32_16x16x32_bf16 v[58:61], v[168:171], v[122:125], v[58:61]
	s_add_u32 s6, s0, 0x22000
	s_addc_u32 s7, s1, 0
	v_lshl_add_u64 v[90:91], v[100:101], 0, s[6:7]
	global_load_dwordx4 v[90:93], v[90:91], off offset:256
	v_mfma_f32_16x16x32_bf16 v[54:57], v[172:175], v[122:125], v[54:57]
	v_mfma_f32_16x16x32_bf16 v[50:53], v[176:179], v[122:125], v[50:53]
	s_waitcnt lgkmcnt(0)
	v_mfma_f32_16x16x32_bf16 v[46:49], v[164:167], v[126:129], v[46:49]
	ds_read_b128 v[180:183], v113 offset:4096
	ds_read_b128 v[184:187], v113 offset:6144
	v_mfma_f32_16x16x32_bf16 v[42:45], v[168:171], v[126:129], v[42:45]
	v_mfma_f32_16x16x32_bf16 v[38:41], v[172:175], v[126:129], v[38:41]
	s_add_u32 vcc_lo, s0, 0x33000
	s_addc_u32 vcc_hi, s1, 0
	v_lshl_add_u64 v[94:95], v[100:101], 0, vcc
	global_load_dwordx4 v[94:97], v[94:95], off offset:256
	v_mfma_f32_16x16x32_bf16 v[34:37], v[176:179], v[126:129], v[34:37]
	s_waitcnt lgkmcnt(1)
	v_mfma_f32_16x16x32_bf16 v[30:33], v[164:167], v[180:183], v[30:33]
	s_waitcnt vmcnt(15)
	ds_write_b128 v110, v[224:227] offset:32768
	v_mfma_f32_16x16x32_bf16 v[26:29], v[168:171], v[180:183], v[26:29]
	s_waitcnt vmcnt(14)
	ds_write_b128 v110, v[228:231] offset:36864
	v_mfma_f32_16x16x32_bf16 v[22:25], v[172:175], v[180:183], v[22:25]
	s_waitcnt vmcnt(13)
	ds_write_b128 v110, v[232:235] offset:40960
	v_mfma_f32_16x16x32_bf16 v[18:21], v[176:179], v[180:183], v[18:21]
	s_waitcnt vmcnt(12)
	ds_write_b128 v110, v[236:239] offset:45056
	s_waitcnt lgkmcnt(4)
	v_mfma_f32_16x16x32_bf16 v[14:17], v[164:167], v[184:187], v[14:17]
	s_waitcnt vmcnt(11)
	ds_write_b128 v190, v[240:243] offset:49168
	v_mfma_f32_16x16x32_bf16 v[10:13], v[168:171], v[184:187], v[10:13]
	s_waitcnt vmcnt(10)
	ds_write_b128 v190, v[244:247] offset:53264
	v_mfma_f32_16x16x32_bf16 v[6:9], v[172:175], v[184:187], v[6:9]
	s_waitcnt vmcnt(9)
	ds_write_b128 v190, v[248:251] offset:57360
	v_mfma_f32_16x16x32_bf16 v[2:5], v[176:179], v[184:187], v[2:5]
	s_waitcnt vmcnt(8)
	ds_write_b128 v190, v[252:255] offset:61456
	s_waitcnt lgkmcnt(0)
	s_barrier
	s_add_u32 s0, s0, 0x80
	s_addc_u32 s1, s1, 0
	ds_read_b128 v[114:117], v188 offset:49168
	ds_read_b128 v[118:121], v188 offset:49680
	ds_read_b128 v[156:159], v188 offset:53264
	ds_read_b128 v[160:163], v188 offset:53776
	ds_read_b128 v[122:125], v112 offset:32768
	ds_read_b128 v[126:129], v112 offset:34816
	v_lshl_add_u64 v[224:225], v[98:99], 0, s[0:1]
	global_load_dwordx4 v[224:227], v[224:225], off offset:256
	s_add_u32 s6, s0, 0x11000
	s_addc_u32 s7, s1, 0
	v_lshl_add_u64 v[228:229], v[98:99], 0, s[6:7]
	global_load_dwordx4 v[228:231], v[228:229], off offset:256
	s_waitcnt lgkmcnt(1)
	v_mfma_f32_16x16x32_bf16 v[66:69], v[114:117], v[122:125], v[66:69]
	v_mfma_f32_16x16x32_bf16 v[58:61], v[118:121], v[122:125], v[58:61]
	s_add_u32 vcc_lo, s0, 0x22000
	s_addc_u32 vcc_hi, s1, 0
	v_lshl_add_u64 v[232:233], v[98:99], 0, vcc
	global_load_dwordx4 v[232:235], v[232:233], off offset:256
	v_mfma_f32_16x16x32_bf16 v[54:57], v[156:159], v[122:125], v[54:57]
	v_mfma_f32_16x16x32_bf16 v[50:53], v[160:163], v[122:125], v[50:53]
	s_waitcnt lgkmcnt(0)
	v_mfma_f32_16x16x32_bf16 v[46:49], v[114:117], v[126:129], v[46:49]
	ds_read_b128 v[180:183], v112 offset:36864
	ds_read_b128 v[184:187], v112 offset:38912
	v_mfma_f32_16x16x32_bf16 v[42:45], v[118:121], v[126:129], v[42:45]
	v_mfma_f32_16x16x32_bf16 v[38:41], v[156:159], v[126:129], v[38:41]
	s_add_u32 s6, s0, 0x33000
	s_addc_u32 s7, s1, 0
	v_lshl_add_u64 v[236:237], v[98:99], 0, s[6:7]
	global_load_dwordx4 v[236:239], v[236:237], off offset:256
	v_mfma_f32_16x16x32_bf16 v[34:37], v[160:163], v[126:129], v[34:37]
	s_waitcnt lgkmcnt(1)
	v_mfma_f32_16x16x32_bf16 v[30:33], v[114:117], v[180:183], v[30:33]
	ds_read_b128 v[164:167], v189 offset:49168
	ds_read_b128 v[168:171], v189 offset:49680
	v_mfma_f32_16x16x32_bf16 v[26:29], v[118:121], v[180:183], v[26:29]
	v_lshl_add_u64 v[240:241], v[100:101], 0, s[0:1]
	global_load_dwordx4 v[240:243], v[240:241], off offset:256
	v_mfma_f32_16x16x32_bf16 v[22:25], v[156:159], v[180:183], v[22:25]
	ds_read_b128 v[172:175], v189 offset:53264
	ds_read_b128 v[176:179], v189 offset:53776
	v_mfma_f32_16x16x32_bf16 v[18:21], v[160:163], v[180:183], v[18:21]
	s_waitcnt lgkmcnt(4)
	v_mfma_f32_16x16x32_bf16 v[14:17], v[114:117], v[184:187], v[14:17]
	ds_read_b128 v[122:125], v113 offset:32768
	ds_read_b128 v[126:129], v113 offset:34816
	v_mfma_f32_16x16x32_bf16 v[10:13], v[118:121], v[184:187], v[10:13]
	v_mfma_f32_16x16x32_bf16 v[6:9], v[156:159], v[184:187], v[6:9]
	s_add_u32 vcc_lo, s0, 0x11000
	s_addc_u32 vcc_hi, s1, 0
	v_lshl_add_u64 v[244:245], v[100:101], 0, vcc
	global_load_dwordx4 v[244:247], v[244:245], off offset:256
	v_mfma_f32_16x16x32_bf16 v[2:5], v[160:163], v[184:187], v[2:5]
	s_waitcnt lgkmcnt(1)
	v_mfma_f32_16x16x32_bf16 v[66:69], v[164:167], v[122:125], v[66:69]
	v_mfma_f32_16x16x32_bf16 v[58:61], v[168:171], v[122:125], v[58:61]
	s_add_u32 s6, s0, 0x22000
	s_addc_u32 s7, s1, 0
	v_lshl_add_u64 v[248:249], v[100:101], 0, s[6:7]
	global_load_dwordx4 v[248:251], v[248:249], off offset:256
	v_mfma_f32_16x16x32_bf16 v[54:57], v[172:175], v[122:125], v[54:57]
	v_mfma_f32_16x16x32_bf16 v[50:53], v[176:179], v[122:125], v[50:53]
	s_waitcnt lgkmcnt(0)
	v_mfma_f32_16x16x32_bf16 v[46:49], v[164:167], v[126:129], v[46:49]
	ds_read_b128 v[180:183], v113 offset:36864
	ds_read_b128 v[184:187], v113 offset:38912
	v_mfma_f32_16x16x32_bf16 v[42:45], v[168:171], v[126:129], v[42:45]
	v_mfma_f32_16x16x32_bf16 v[38:41], v[172:175], v[126:129], v[38:41]
	s_add_u32 vcc_lo, s0, 0x33000
	s_addc_u32 vcc_hi, s1, 0
	v_lshl_add_u64 v[252:253], v[100:101], 0, vcc
	global_load_dwordx4 v[252:255], v[252:253], off offset:256
	v_mfma_f32_16x16x32_bf16 v[34:37], v[176:179], v[126:129], v[34:37]
	s_waitcnt lgkmcnt(1)
	v_mfma_f32_16x16x32_bf16 v[30:33], v[164:167], v[180:183], v[30:33]
	s_waitcnt vmcnt(15)
	ds_write_b128 v110, v[62:65]
	v_mfma_f32_16x16x32_bf16 v[26:29], v[168:171], v[180:183], v[26:29]
	s_waitcnt vmcnt(14)
	ds_write_b128 v110, v[70:73] offset:4096
	v_mfma_f32_16x16x32_bf16 v[22:25], v[172:175], v[180:183], v[22:25]
	s_waitcnt vmcnt(13)
	ds_write_b128 v110, v[74:77] offset:8192
	v_mfma_f32_16x16x32_bf16 v[18:21], v[176:179], v[180:183], v[18:21]
	s_waitcnt vmcnt(12)
	ds_write_b128 v110, v[78:81] offset:12288
	s_waitcnt lgkmcnt(4)
	v_mfma_f32_16x16x32_bf16 v[14:17], v[164:167], v[184:187], v[14:17]
	s_waitcnt vmcnt(11)
	ds_write_b128 v190, v[82:85] offset:16384
	v_mfma_f32_16x16x32_bf16 v[10:13], v[168:171], v[184:187], v[10:13]
	s_waitcnt vmcnt(10)
	ds_write_b128 v190, v[86:89] offset:20480
	v_mfma_f32_16x16x32_bf16 v[6:9], v[172:175], v[184:187], v[6:9]
	s_waitcnt vmcnt(9)
	ds_write_b128 v190, v[90:93] offset:24576
	v_mfma_f32_16x16x32_bf16 v[2:5], v[176:179], v[184:187], v[2:5]
	s_waitcnt vmcnt(8)
	ds_write_b128 v190, v[94:97] offset:28672
	s_waitcnt lgkmcnt(0)
	s_barrier
	s_add_u32 s0, s0, 0x80
	s_addc_u32 s1, s1, 0
	s_cmpk_lg_i32 s0, 0x700
	s_cbranch_scc1 .Lgq_c
	ds_read_b128 v[114:117], v188 offset:16384
	ds_read_b128 v[118:121], v188 offset:16896
	ds_read_b128 v[156:159], v188 offset:20480
	ds_read_b128 v[160:163], v188 offset:20992
	ds_read_b128 v[122:125], v112
	ds_read_b128 v[126:129], v112 offset:2048
	s_waitcnt lgkmcnt(1)
	v_mfma_f32_16x16x32_bf16 v[66:69], v[114:117], v[122:125], v[66:69]
	v_mfma_f32_16x16x32_bf16 v[58:61], v[118:121], v[122:125], v[58:61]
	v_mfma_f32_16x16x32_bf16 v[54:57], v[156:159], v[122:125], v[54:57]
	v_mfma_f32_16x16x32_bf16 v[50:53], v[160:163], v[122:125], v[50:53]
	s_waitcnt lgkmcnt(0)
	v_mfma_f32_16x16x32_bf16 v[46:49], v[114:117], v[126:129], v[46:49]
	ds_read_b128 v[180:183], v112 offset:4096
	ds_read_b128 v[184:187], v112 offset:6144
	v_mfma_f32_16x16x32_bf16 v[42:45], v[118:121], v[126:129], v[42:45]
	v_mfma_f32_16x16x32_bf16 v[38:41], v[156:159], v[126:129], v[38:41]
	v_mfma_f32_16x16x32_bf16 v[34:37], v[160:163], v[126:129], v[34:37]
	s_waitcnt lgkmcnt(1)
	v_mfma_f32_16x16x32_bf16 v[30:33], v[114:117], v[180:183], v[30:33]
	ds_read_b128 v[164:167], v189 offset:16384
	ds_read_b128 v[168:171], v189 offset:16896
	v_mfma_f32_16x16x32_bf16 v[26:29], v[118:121], v[180:183], v[26:29]
	v_mfma_f32_16x16x32_bf16 v[22:25], v[156:159], v[180:183], v[22:25]
	ds_read_b128 v[172:175], v189 offset:20480
	ds_read_b128 v[176:179], v189 offset:20992
	v_mfma_f32_16x16x32_bf16 v[18:21], v[160:163], v[180:183], v[18:21]
	s_waitcnt lgkmcnt(4)
	v_mfma_f32_16x16x32_bf16 v[14:17], v[114:117], v[184:187], v[14:17]
	ds_read_b128 v[122:125], v113
	ds_read_b128 v[126:129], v113 offset:2048
	v_mfma_f32_16x16x32_bf16 v[10:13], v[118:121], v[184:187], v[10:13]
	v_mfma_f32_16x16x32_bf16 v[6:9], v[156:159], v[184:187], v[6:9]
	v_mfma_f32_16x16x32_bf16 v[2:5], v[160:163], v[184:187], v[2:5]
	s_waitcnt lgkmcnt(1)
	v_mfma_f32_16x16x32_bf16 v[66:69], v[164:167], v[122:125], v[66:69]
	v_mfma_f32_16x16x32_bf16 v[58:61], v[168:171], v[122:125], v[58:61]
	v_mfma_f32_16x16x32_bf16 v[54:57], v[172:175], v[122:125], v[54:57]
	v_mfma_f32_16x16x32_bf16 v[50:53], v[176:179], v[122:125], v[50:53]
	s_waitcnt lgkmcnt(0)
	v_mfma_f32_16x16x32_bf16 v[46:49], v[164:167], v[126:129], v[46:49]
	ds_read_b128 v[180:183], v113 offset:4096
	ds_read_b128 v[184:187], v113 offset:6144
	v_mfma_f32_16x16x32_bf16 v[42:45], v[168:171], v[126:129], v[42:45]
	v_mfma_f32_16x16x32_bf16 v[38:41], v[172:175], v[126:129], v[38:41]
	v_mfma_f32_16x16x32_bf16 v[34:37], v[176:179], v[126:129], v[34:37]
	s_waitcnt lgkmcnt(1)
	v_mfma_f32_16x16x32_bf16 v[30:33], v[164:167], v[180:183], v[30:33]
	s_waitcnt vmcnt(7)
	ds_write_b128 v110, v[224:227] offset:32768
	v_mfma_f32_16x16x32_bf16 v[26:29], v[168:171], v[180:183], v[26:29]
	s_waitcnt vmcnt(6)
	ds_write_b128 v110, v[228:231] offset:36864
	v_mfma_f32_16x16x32_bf16 v[22:25], v[172:175], v[180:183], v[22:25]
	s_waitcnt vmcnt(5)
	ds_write_b128 v110, v[232:235] offset:40960
	v_mfma_f32_16x16x32_bf16 v[18:21], v[176:179], v[180:183], v[18:21]
	s_waitcnt vmcnt(4)
	ds_write_b128 v110, v[236:239] offset:45056
	s_waitcnt lgkmcnt(4)
	v_mfma_f32_16x16x32_bf16 v[14:17], v[164:167], v[184:187], v[14:17]
	s_waitcnt vmcnt(3)
	ds_write_b128 v190, v[240:243] offset:49168
	v_mfma_f32_16x16x32_bf16 v[10:13], v[168:171], v[184:187], v[10:13]
	s_waitcnt vmcnt(2)
	ds_write_b128 v190, v[244:247] offset:53264
	v_mfma_f32_16x16x32_bf16 v[6:9], v[172:175], v[184:187], v[6:9]
	s_waitcnt vmcnt(1)
	ds_write_b128 v190, v[248:251] offset:57360
	v_mfma_f32_16x16x32_bf16 v[2:5], v[176:179], v[184:187], v[2:5]
	s_waitcnt vmcnt(0)
	ds_write_b128 v190, v[252:255] offset:61456
	s_waitcnt lgkmcnt(0)
	s_barrier
	ds_read_b128 v[114:117], v188 offset:49168
	ds_read_b128 v[118:121], v188 offset:49680
	ds_read_b128 v[156:159], v188 offset:53264
	ds_read_b128 v[160:163], v188 offset:53776
	ds_read_b128 v[122:125], v112 offset:32768
	ds_read_b128 v[126:129], v112 offset:34816
	s_waitcnt lgkmcnt(1)
	v_mfma_f32_16x16x32_bf16 v[66:69], v[114:117], v[122:125], v[66:69]
	v_mfma_f32_16x16x32_bf16 v[58:61], v[118:121], v[122:125], v[58:61]
	v_mfma_f32_16x16x32_bf16 v[54:57], v[156:159], v[122:125], v[54:57]
	v_mfma_f32_16x16x32_bf16 v[50:53], v[160:163], v[122:125], v[50:53]
	s_waitcnt lgkmcnt(0)
	v_mfma_f32_16x16x32_bf16 v[46:49], v[114:117], v[126:129], v[46:49]
	ds_read_b128 v[180:183], v112 offset:36864
	ds_read_b128 v[184:187], v112 offset:38912
	v_mfma_f32_16x16x32_bf16 v[42:45], v[118:121], v[126:129], v[42:45]
	v_mfma_f32_16x16x32_bf16 v[38:41], v[156:159], v[126:129], v[38:41]
	v_mfma_f32_16x16x32_bf16 v[34:37], v[160:163], v[126:129], v[34:37]
	s_waitcnt lgkmcnt(1)
	v_mfma_f32_16x16x32_bf16 v[30:33], v[114:117], v[180:183], v[30:33]
	ds_read_b128 v[164:167], v189 offset:49168
	ds_read_b128 v[168:171], v189 offset:49680
	v_mfma_f32_16x16x32_bf16 v[26:29], v[118:121], v[180:183], v[26:29]
	v_mfma_f32_16x16x32_bf16 v[22:25], v[156:159], v[180:183], v[22:25]
	ds_read_b128 v[172:175], v189 offset:53264
	ds_read_b128 v[176:179], v189 offset:53776
	v_mfma_f32_16x16x32_bf16 v[18:21], v[160:163], v[180:183], v[18:21]
	s_waitcnt lgkmcnt(4)
	v_mfma_f32_16x16x32_bf16 v[14:17], v[114:117], v[184:187], v[14:17]
	ds_read_b128 v[122:125], v113 offset:32768
	ds_read_b128 v[126:129], v113 offset:34816
	v_mfma_f32_16x16x32_bf16 v[10:13], v[118:121], v[184:187], v[10:13]
	v_mfma_f32_16x16x32_bf16 v[6:9], v[156:159], v[184:187], v[6:9]
	v_mfma_f32_16x16x32_bf16 v[2:5], v[160:163], v[184:187], v[2:5]
	s_waitcnt lgkmcnt(1)
	v_mfma_f32_16x16x32_bf16 v[66:69], v[164:167], v[122:125], v[66:69]
	v_mfma_f32_16x16x32_bf16 v[58:61], v[168:171], v[122:125], v[58:61]
	v_mfma_f32_16x16x32_bf16 v[54:57], v[172:175], v[122:125], v[54:57]
	v_mfma_f32_16x16x32_bf16 v[50:53], v[176:179], v[122:125], v[50:53]
	s_waitcnt lgkmcnt(0)
	v_mfma_f32_16x16x32_bf16 v[46:49], v[164:167], v[126:129], v[46:49]
	ds_read_b128 v[180:183], v113 offset:36864
	ds_read_b128 v[184:187], v113 offset:38912
	v_mfma_f32_16x16x32_bf16 v[42:45], v[168:171], v[126:129], v[42:45]
	v_mfma_f32_16x16x32_bf16 v[38:41], v[172:175], v[126:129], v[38:41]
	v_mfma_f32_16x16x32_bf16 v[34:37], v[176:179], v[126:129], v[34:37]
	s_waitcnt lgkmcnt(1)
	v_mfma_f32_16x16x32_bf16 v[30:33], v[164:167], v[180:183], v[30:33]
	v_mfma_f32_16x16x32_bf16 v[26:29], v[168:171], v[180:183], v[26:29]
	v_mfma_f32_16x16x32_bf16 v[22:25], v[172:175], v[180:183], v[22:25]
	v_mfma_f32_16x16x32_bf16 v[18:21], v[176:179], v[180:183], v[18:21]
	s_waitcnt lgkmcnt(0)
	v_mfma_f32_16x16x32_bf16 v[14:17], v[164:167], v[184:187], v[14:17]
	v_mfma_f32_16x16x32_bf16 v[10:13], v[168:171], v[184:187], v[10:13]
	v_mfma_f32_16x16x32_bf16 v[6:9], v[172:175], v[184:187], v[6:9]
	v_mfma_f32_16x16x32_bf16 v[2:5], v[176:179], v[184:187], v[2:5]
	s_barrier

.LBB0_521:
	s_cmp_lt_i32 s41, 6
	s_cbranch_scc0 .LBB0_203
	s_lshl_b32 s0, s41, 6
	s_and_b32 s0, s0, 64
	s_add_i32 s12, s42, s0
	v_mov_b32_e32 v1, v0
	s_lshl_b32 s13, s12, 6
	s_ashr_i32 s41, s41, 1
	s_lshl_b32 s14, s41, 7
	s_waitcnt vmcnt(4)
	v_ashrrev_i32_e32 v8, 3, v1
	v_and_b32_e32 v9, 7, v1
	v_add_u32_e32 v4, s13, v8
	v_mov_b64_e32 v[2:3], s[66:67]
	s_addk_i32 s14, 0xc00
	v_mad_i64_i32 v[2:3], s[0:1], v4, s58, v[2:3]
	v_lshlrev_b32_e32 v106, 4, v9
	v_lshl_add_u64 v[58:59], v[2:3], 0, v[106:107]
	v_add_u32_e32 v4, s14, v8
	v_mov_b64_e32 v[2:3], s[2:3]
	v_mad_i64_i32 v[2:3], s[0:1], v4, s58, v[2:3]
	s_mov_b32 s0, 0x11000
	s_nop 0
	v_add_co_u32_e32 v4, vcc, s0, v58
	v_lshl_add_u64 v[60:61], v[2:3], 0, v[106:107]
	s_nop 0
	v_addc_co_u32_e32 v5, vcc, 0, v59, vcc
	v_add_co_u32_e32 v2, vcc, s0, v60
	s_mov_b32 s0, 0x22000
	s_nop 0
	v_addc_co_u32_e32 v3, vcc, 0, v61, vcc
	v_add_co_u32_e32 v6, vcc, s0, v60
	s_mov_b32 s0, 0x33000
	s_nop 0
	v_addc_co_u32_e32 v7, vcc, 0, v61, vcc
	global_load_dwordx4 v[34:37], v[58:59], off
	global_load_dwordx4 v[38:41], v[60:61], off
	global_load_dwordx4 v[42:45], v[2:3], off
	global_load_dwordx4 v[50:53], v[6:7], off
	v_add_co_u32_e32 v2, vcc, s0, v60
	s_waitcnt vmcnt(7)
	v_ashrrev_i32_e32 v11, 4, v1
	v_addc_co_u32_e32 v3, vcc, 0, v61, vcc
	global_load_dwordx4 v[54:57], v[2:3], off
	global_load_dwordx4 v[46:49], v[4:5], off
	v_lshrrev_b32_e32 v12, 5, v1
	v_lshrrev_b32_e32 v10, 4, v1
	v_bfe_u32 v62, v1, 4, 2
	v_bfe_u32 v13, v1, 1, 3
	s_waitcnt vmcnt(8)
	v_xor_b32_e32 v16, v11, v1
	v_and_b32_e32 v11, 1, v11
	v_and_b32_e32 v12, 6, v12
	v_ashrrev_i32_e32 v63, 7, v1
	v_lshlrev_b32_e32 v65, 7, v8
	v_bitop3_b32 v8, v10, v13, 3 bitop3:0x6c
	v_bitop3_b32 v13, v62, v13, 4 bitop3:0x36
	v_bitop3_b32 v9, v11, v9, v12 bitop3:0x36
	v_and_b32_e32 v64, 15, v1
	v_lshlrev_b32_e32 v14, 1, v1
	v_and_b32_e32 v15, 0x43, v1
	v_lshlrev_b32_e32 v10, 12, v63
	v_lshlrev_b32_e32 v66, 4, v8
	v_lshlrev_b32_e32 v68, 4, v13
	v_lshlrev_b32_e32 v70, 4, v9
	v_mov_b32_e32 v2, 0
	v_lshlrev_b32_e32 v17, 7, v64
	v_and_or_b32 v14, v14, 24, v15
	v_lshlrev_b32_e32 v11, 4, v16
	s_movk_i32 s4, 0x70
	v_or_b32_e32 v8, v66, v10
	v_or_b32_e32 v9, v68, v10
	v_or_b32_e32 v10, v65, v70
	s_mov_b64 s[0:1], 0
	v_mov_b32_e32 v3, v2
	v_mov_b32_e32 v4, v2
	v_mov_b32_e32 v5, v2
	v_mov_b32_e32 v6, v2
	v_mov_b32_e32 v7, v2
	v_lshlrev_b32_e32 v67, 7, v14
	v_and_or_b32 v69, v11, s4, v65
	v_add_u32_e32 v71, v8, v17
	v_add_u32_e32 v72, v9, v17
	v_mov_b32_e32 v8, v2
	v_mov_b32_e32 v9, v2
	v_mov_b32_e32 v11, v2
	v_mov_b32_e32 v12, v2
	v_mov_b32_e32 v13, v2
	v_mov_b32_e32 v14, v2
	v_mov_b32_e32 v15, v2
	v_mov_b32_e32 v16, v2
	v_mov_b32_e32 v17, v2
	v_mov_b32_e32 v18, v2
	v_mov_b32_e32 v19, v2
	v_mov_b32_e32 v20, v2
	v_mov_b32_e32 v21, v2
	v_mov_b32_e32 v22, v2
	s_waitcnt vmcnt(4)
	ds_write_b128 v10, v[38:41] offset:16384
	ds_write_b128 v69, v[34:37]
	s_waitcnt vmcnt(3)
	ds_write_b128 v10, v[42:45] offset:20480
	s_waitcnt vmcnt(2)
	ds_write_b128 v10, v[50:53] offset:24576
	s_waitcnt vmcnt(1)
	ds_write_b128 v10, v[54:57] offset:28672
	s_waitcnt vmcnt(0)
	ds_write_b128 v69, v[46:49] offset:4096
	v_mov_b32_e32 v10, v2
	v_mov_b32_e32 v23, v2
	v_mov_b32_e32 v24, v2
	v_mov_b32_e32 v25, v2
	v_mov_b32_e32 v26, v2
	v_mov_b32_e32 v27, v2
	v_mov_b32_e32 v28, v2
	v_mov_b32_e32 v29, v2
	v_mov_b32_e32 v30, v2
	v_mov_b32_e32 v31, v2
	v_mov_b32_e32 v32, v2
	v_mov_b32_e32 v33, v2
	v_lshl_add_u64 v[224:225], v[58:59], 0, s[0:1]
	global_load_dwordx4 v[224:227], v[224:225], off offset:128
	s_add_u32 s6, s0, 0x11000
	s_addc_u32 s7, s1, 0
	v_lshl_add_u64 v[228:229], v[58:59], 0, s[6:7]
	global_load_dwordx4 v[228:231], v[228:229], off offset:128
	v_lshl_add_u64 v[232:233], v[60:61], 0, s[0:1]
	global_load_dwordx4 v[232:235], v[232:233], off offset:128
	s_add_u32 vcc_lo, s0, 0x11000
	s_addc_u32 vcc_hi, s1, 0
	v_lshl_add_u64 v[236:237], v[60:61], 0, vcc
	global_load_dwordx4 v[236:239], v[236:237], off offset:128
	s_add_u32 s6, s0, 0x22000
	s_addc_u32 s7, s1, 0
	v_lshl_add_u64 v[240:241], v[60:61], 0, s[6:7]
	global_load_dwordx4 v[240:243], v[240:241], off offset:128
	s_add_u32 vcc_lo, s0, 0x33000
	s_addc_u32 vcc_hi, s1, 0
	v_lshl_add_u64 v[244:245], v[60:61], 0, vcc
	global_load_dwordx4 v[244:247], v[244:245], off offset:128
	v_add_u32_e32 v188, v66, v67
	v_add_u32_e32 v189, v68, v67
	v_add_u32_e32 v190, v65, v70
	s_waitcnt lgkmcnt(0)
	s_barrier
	s_branch .LBB0_524
.LBB0_524:
.Lgq_h:
	ds_read_b128 v[74:77], v188 offset:16384
	ds_read_b128 v[78:81], v188 offset:16896
	ds_read_b128 v[90:93], v188 offset:20480
	ds_read_b128 v[94:97], v188 offset:20992
	ds_read_b128 v[82:85], v71
	ds_read_b128 v[86:89], v71 offset:2048
	ds_read_b128 v[164:167], v189 offset:16384
	ds_read_b128 v[168:171], v189 offset:16896
	ds_read_b128 v[180:183], v72
	v_lshl_add_u64 v[34:35], v[58:59], 0, s[0:1]
	global_load_dwordx4 v[34:37], v[34:35], off offset:256
	s_add_u32 s6, s0, 0x11000
	s_addc_u32 s7, s1, 0
	v_lshl_add_u64 v[46:47], v[58:59], 0, s[6:7]
	global_load_dwordx4 v[46:49], v[46:47], off offset:256
	s_waitcnt lgkmcnt(4)
	v_mfma_f32_16x16x32_bf16 v[30:33], v[74:77], v[82:85], v[30:33]
	ds_read_b128 v[172:175], v189 offset:20480
	ds_read_b128 v[176:179], v189 offset:20992
	v_mfma_f32_16x16x32_bf16 v[26:29], v[78:81], v[82:85], v[26:29]
	v_lshl_add_u64 v[38:39], v[60:61], 0, s[0:1]
	global_load_dwordx4 v[38:41], v[38:39], off offset:256
	v_mfma_f32_16x16x32_bf16 v[22:25], v[90:93], v[82:85], v[22:25]
	ds_read_b128 v[184:187], v72 offset:2048
	v_mfma_f32_16x16x32_bf16 v[18:21], v[94:97], v[82:85], v[18:21]
	s_add_u32 vcc_lo, s0, 0x11000
	s_addc_u32 vcc_hi, s1, 0
	v_lshl_add_u64 v[42:43], v[60:61], 0, vcc
	global_load_dwordx4 v[42:45], v[42:43], off offset:256
	s_waitcnt lgkmcnt(6)
	v_mfma_f32_16x16x32_bf16 v[14:17], v[74:77], v[86:89], v[14:17]
	s_add_u32 s6, s0, 0x22000
	s_addc_u32 s7, s1, 0
	v_lshl_add_u64 v[50:51], v[60:61], 0, s[6:7]
	global_load_dwordx4 v[50:53], v[50:51], off offset:256
	v_mfma_f32_16x16x32_bf16 v[10:13], v[78:81], v[86:89], v[10:13]
	v_mfma_f32_16x16x32_bf16 v[6:9], v[90:93], v[86:89], v[6:9]
	s_add_u32 vcc_lo, s0, 0x33000
	s_addc_u32 vcc_hi, s1, 0
	v_lshl_add_u64 v[54:55], v[60:61], 0, vcc
	global_load_dwordx4 v[54:57], v[54:55], off offset:256
	v_mfma_f32_16x16x32_bf16 v[2:5], v[94:97], v[86:89], v[2:5]
	s_waitcnt lgkmcnt(1)
	v_mfma_f32_16x16x32_bf16 v[30:33], v[164:167], v[180:183], v[30:33]
	s_waitcnt vmcnt(11)
	ds_write_b128 v69, v[224:227] offset:32768
	v_mfma_f32_16x16x32_bf16 v[26:29], v[168:171], v[180:183], v[26:29]
	s_waitcnt vmcnt(10)
	ds_write_b128 v69, v[228:231] offset:36864
	v_mfma_f32_16x16x32_bf16 v[22:25], v[172:175], v[180:183], v[22:25]
	s_waitcnt vmcnt(9)
	ds_write_b128 v190, v[232:235] offset:49168
	v_mfma_f32_16x16x32_bf16 v[18:21], v[176:179], v[180:183], v[18:21]
	s_waitcnt vmcnt(8)
	ds_write_b128 v190, v[236:239] offset:53264
	s_waitcnt lgkmcnt(4)
	v_mfma_f32_16x16x32_bf16 v[14:17], v[164:167], v[184:187], v[14:17]
	s_waitcnt vmcnt(7)
	ds_write_b128 v190, v[240:243] offset:57360
	v_mfma_f32_16x16x32_bf16 v[10:13], v[168:171], v[184:187], v[10:13]
	s_waitcnt vmcnt(6)
	ds_write_b128 v190, v[244:247] offset:61456
	v_mfma_f32_16x16x32_bf16 v[6:9], v[172:175], v[184:187], v[6:9]
	v_mfma_f32_16x16x32_bf16 v[2:5], v[176:179], v[184:187], v[2:5]
	s_waitcnt lgkmcnt(0)
	s_barrier
	s_add_u32 s0, s0, 0x80
	s_addc_u32 s1, s1, 0
	ds_read_b128 v[74:77], v188 offset:49168
	ds_read_b128 v[78:81], v188 offset:49680
	ds_read_b128 v[90:93], v188 offset:53264
	ds_read_b128 v[94:97], v188 offset:53776
	ds_read_b128 v[82:85], v71 offset:32768
	ds_read_b128 v[86:89], v71 offset:34816
	ds_read_b128 v[164:167], v189 offset:49168
	ds_read_b128 v[168:171], v189 offset:49680
	ds_read_b128 v[180:183], v72 offset:32768
	v_lshl_add_u64 v[224:225], v[58:59], 0, s[0:1]
	global_load_dwordx4 v[224:227], v[224:225], off offset:256
	s_add_u32 s6, s0, 0x11000
	s_addc_u32 s7, s1, 0
	v_lshl_add_u64 v[228:229], v[58:59], 0, s[6:7]
	global_load_dwordx4 v[228:231], v[228:229], off offset:256
	s_waitcnt lgkmcnt(4)
	v_mfma_f32_16x16x32_bf16 v[30:33], v[74:77], v[82:85], v[30:33]
	ds_read_b128 v[172:175], v189 offset:53264
	ds_read_b128 v[176:179], v189 offset:53776
	v_mfma_f32_16x16x32_bf16 v[26:29], v[78:81], v[82:85], v[26:29]
	v_lshl_add_u64 v[232:233], v[60:61], 0, s[0:1]
	global_load_dwordx4 v[232:235], v[232:233], off offset:256
	v_mfma_f32_16x16x32_bf16 v[22:25], v[90:93], v[82:85], v[22:25]
	ds_read_b128 v[184:187], v72 offset:34816
	v_mfma_f32_16x16x32_bf16 v[18:21], v[94:97], v[82:85], v[18:21]
	s_add_u32 vcc_lo, s0, 0x11000
	s_addc_u32 vcc_hi, s1, 0
	v_lshl_add_u64 v[236:237], v[60:61], 0, vcc
	global_load_dwordx4 v[236:239], v[236:237], off offset:256
	s_waitcnt lgkmcnt(6)
	v_mfma_f32_16x16x32_bf16 v[14:17], v[74:77], v[86:89], v[14:17]
	s_add_u32 s6, s0, 0x22000
	s_addc_u32 s7, s1, 0
	v_lshl_add_u64 v[240:241], v[60:61], 0, s[6:7]
	global_load_dwordx4 v[240:243], v[240:241], off offset:256
	v_mfma_f32_16x16x32_bf16 v[10:13], v[78:81], v[86:89], v[10:13]
	v_mfma_f32_16x16x32_bf16 v[6:9], v[90:93], v[86:89], v[6:9]
	s_add_u32 vcc_lo, s0, 0x33000
	s_addc_u32 vcc_hi, s1, 0
	v_lshl_add_u64 v[244:245], v[60:61], 0, vcc
	global_load_dwordx4 v[244:247], v[244:245], off offset:256
	v_mfma_f32_16x16x32_bf16 v[2:5], v[94:97], v[86:89], v[2:5]
	s_waitcnt lgkmcnt(1)
	v_mfma_f32_16x16x32_bf16 v[30:33], v[164:167], v[180:183], v[30:33]
	s_waitcnt vmcnt(11)
	ds_write_b128 v69, v[34:37]
	v_mfma_f32_16x16x32_bf16 v[26:29], v[168:171], v[180:183], v[26:29]
	s_waitcnt vmcnt(10)
	ds_write_b128 v69, v[46:49] offset:4096
	v_mfma_f32_16x16x32_bf16 v[22:25], v[172:175], v[180:183], v[22:25]
	s_waitcnt vmcnt(9)
	ds_write_b128 v190, v[38:41] offset:16384
	v_mfma_f32_16x16x32_bf16 v[18:21], v[176:179], v[180:183], v[18:21]
	s_waitcnt vmcnt(8)
	ds_write_b128 v190, v[42:45] offset:20480
	s_waitcnt lgkmcnt(4)
	v_mfma_f32_16x16x32_bf16 v[14:17], v[164:167], v[184:187], v[14:17]
	s_waitcnt vmcnt(7)
	ds_write_b128 v190, v[50:53] offset:24576
	v_mfma_f32_16x16x32_bf16 v[10:13], v[168:171], v[184:187], v[10:13]
	s_waitcnt vmcnt(6)
	ds_write_b128 v190, v[54:57] offset:28672
	v_mfma_f32_16x16x32_bf16 v[6:9], v[172:175], v[184:187], v[6:9]
	v_mfma_f32_16x16x32_bf16 v[2:5], v[176:179], v[184:187], v[2:5]
	s_waitcnt lgkmcnt(0)
	s_barrier
	s_add_u32 s0, s0, 0x80
	s_addc_u32 s1, s1, 0
	s_cmpk_lg_i32 s0, 0x700
	s_cbranch_scc1 .Lgq_h
	ds_read_b128 v[74:77], v188 offset:16384
	ds_read_b128 v[78:81], v188 offset:16896
	ds_read_b128 v[90:93], v188 offset:20480
	ds_read_b128 v[94:97], v188 offset:20992
	ds_read_b128 v[82:85], v71
	ds_read_b128 v[86:89], v71 offset:2048
	ds_read_b128 v[164:167], v189 offset:16384
	ds_read_b128 v[168:171], v189 offset:16896
	ds_read_b128 v[180:183], v72
	s_waitcnt lgkmcnt(4)
	v_mfma_f32_16x16x32_bf16 v[30:33], v[74:77], v[82:85], v[30:33]
	ds_read_b128 v[172:175], v189 offset:20480
	ds_read_b128 v[176:179], v189 offset:20992
	v_mfma_f32_16x16x32_bf16 v[26:29], v[78:81], v[82:85], v[26:29]
	v_mfma_f32_16x16x32_bf16 v[22:25], v[90:93], v[82:85], v[22:25]
	ds_read_b128 v[184:187], v72 offset:2048
	v_mfma_f32_16x16x32_bf16 v[18:21], v[94:97], v[82:85], v[18:21]
	s_waitcnt lgkmcnt(6)
	v_mfma_f32_16x16x32_bf16 v[14:17], v[74:77], v[86:89], v[14:17]
	v_mfma_f32_16x16x32_bf16 v[10:13], v[78:81], v[86:89], v[10:13]
	v_mfma_f32_16x16x32_bf16 v[6:9], v[90:93], v[86:89], v[6:9]
	v_mfma_f32_16x16x32_bf16 v[2:5], v[94:97], v[86:89], v[2:5]
	s_waitcnt lgkmcnt(1)
	v_mfma_f32_16x16x32_bf16 v[30:33], v[164:167], v[180:183], v[30:33]
	s_waitcnt vmcnt(5)
	ds_write_b128 v69, v[224:227] offset:32768
	v_mfma_f32_16x16x32_bf16 v[26:29], v[168:171], v[180:183], v[26:29]
	s_waitcnt vmcnt(4)
	ds_write_b128 v69, v[228:231] offset:36864
	v_mfma_f32_16x16x32_bf16 v[22:25], v[172:175], v[180:183], v[22:25]
	s_waitcnt vmcnt(3)
	ds_write_b128 v190, v[232:235] offset:49168
	v_mfma_f32_16x16x32_bf16 v[18:21], v[176:179], v[180:183], v[18:21]
	s_waitcnt vmcnt(2)
	ds_write_b128 v190, v[236:239] offset:53264
	s_waitcnt lgkmcnt(4)
	v_mfma_f32_16x16x32_bf16 v[14:17], v[164:167], v[184:187], v[14:17]
	s_waitcnt vmcnt(1)
	ds_write_b128 v190, v[240:243] offset:57360
	v_mfma_f32_16x16x32_bf16 v[10:13], v[168:171], v[184:187], v[10:13]
	s_waitcnt vmcnt(0)
	ds_write_b128 v190, v[244:247] offset:61456
	v_mfma_f32_16x16x32_bf16 v[6:9], v[172:175], v[184:187], v[6:9]
	v_mfma_f32_16x16x32_bf16 v[2:5], v[176:179], v[184:187], v[2:5]
	s_waitcnt lgkmcnt(0)
	s_barrier
	ds_read_b128 v[74:77], v188 offset:49168
	ds_read_b128 v[78:81], v188 offset:49680
	ds_read_b128 v[90:93], v188 offset:53264
	ds_read_b128 v[94:97], v188 offset:53776
	ds_read_b128 v[82:85], v71 offset:32768
	ds_read_b128 v[86:89], v71 offset:34816
	ds_read_b128 v[164:167], v189 offset:49168
	ds_read_b128 v[168:171], v189 offset:49680
	ds_read_b128 v[180:183], v72 offset:32768
	s_waitcnt lgkmcnt(4)
	v_mfma_f32_16x16x32_bf16 v[30:33], v[74:77], v[82:85], v[30:33]
	ds_read_b128 v[172:175], v189 offset:53264
	ds_read_b128 v[176:179], v189 offset:53776
	v_mfma_f32_16x16x32_bf16 v[26:29], v[78:81], v[82:85], v[26:29]
	v_mfma_f32_16x16x32_bf16 v[22:25], v[90:93], v[82:85], v[22:25]
	ds_read_b128 v[184:187], v72 offset:34816
	v_mfma_f32_16x16x32_bf16 v[18:21], v[94:97], v[82:85], v[18:21]
	s_waitcnt lgkmcnt(6)
	v_mfma_f32_16x16x32_bf16 v[14:17], v[74:77], v[86:89], v[14:17]
	v_mfma_f32_16x16x32_bf16 v[10:13], v[78:81], v[86:89], v[10:13]
	v_mfma_f32_16x16x32_bf16 v[6:9], v[90:93], v[86:89], v[6:9]
	v_mfma_f32_16x16x32_bf16 v[2:5], v[94:97], v[86:89], v[2:5]
	s_waitcnt lgkmcnt(1)
	v_mfma_f32_16x16x32_bf16 v[30:33], v[164:167], v[180:183], v[30:33]
	v_mfma_f32_16x16x32_bf16 v[26:29], v[168:171], v[180:183], v[26:29]
	v_mfma_f32_16x16x32_bf16 v[22:25], v[172:175], v[180:183], v[22:25]
	v_mfma_f32_16x16x32_bf16 v[18:21], v[176:179], v[180:183], v[18:21]
	s_waitcnt lgkmcnt(0)
	v_mfma_f32_16x16x32_bf16 v[14:17], v[164:167], v[184:187], v[14:17]
	v_mfma_f32_16x16x32_bf16 v[10:13], v[168:171], v[184:187], v[10:13]
	v_mfma_f32_16x16x32_bf16 v[6:9], v[172:175], v[184:187], v[6:9]
	v_mfma_f32_16x16x32_bf16 v[2:5], v[176:179], v[184:187], v[2:5]
	s_barrier

.LBB0_1384:
	s_abs_i32 s11, s39
	s_mul_hi_u32 s12, s11, s46
	s_mul_i32 s13, s12, s43
	s_ashr_i32 s10, s39, 31
	s_sub_i32 s11, s11, s13
	s_xor_b32 s10, s10, s45
	s_add_i32 s13, s12, 1
	s_sub_i32 s14, s11, s43
	s_cmp_ge_u32 s11, s43
	s_cselect_b32 s12, s13, s12
	s_cselect_b32 s11, s14, s11
	s_add_i32 s13, s12, 1
	s_cmp_ge_u32 s11, s43
	s_cselect_b32 s11, s13, s12
	s_xor_b32 s11, s11, s10
	s_sub_i32 s10, s11, s10
	v_mov_b32_e32 v1, v0
	s_lshl_b32 s47, s10, 7
	s_mul_i32 s10, s10, s40
	s_sub_i32 s10, s39, s10
	s_waitcnt vmcnt(1)
	v_ashrrev_i32_e32 v34, 3, v1
	v_and_b32_e32 v35, 7, v1
	v_add_u32_e32 v4, s47, v34
	v_mov_b64_e32 v[2:3], s[66:67]
	s_lshl_b32 s48, s10, 10
	v_mad_i64_i32 v[2:3], s[10:11], v4, s58, v[2:3]
	v_lshlrev_b32_e32 v106, 4, v35
	v_lshl_add_u64 v[98:99], v[2:3], 0, v[106:107]
	s_mov_b32 s4, 0x11000
	v_add_co_u32_e32 v6, vcc, s4, v98
	s_mov_b32 s5, 0x22000
	s_nop 0
	v_addc_co_u32_e32 v7, vcc, 0, v99, vcc
	s_add_i32 s48, s48, s44
	v_add_co_u32_e32 v10, vcc, s5, v98
	v_add_u32_e32 v4, s48, v34
	v_mov_b64_e32 v[2:3], s[0:1]
	v_addc_co_u32_e32 v11, vcc, 0, v99, vcc
	s_mov_b32 s8, 0x33000
	v_mad_i64_i32 v[18:19], s[10:11], v4, s58, v[2:3]
	v_add_co_u32_e32 v14, vcc, s8, v98
	v_lshl_add_u64 v[100:101], v[18:19], 0, v[106:107]
	s_nop 0
	v_addc_co_u32_e32 v15, vcc, 0, v99, vcc
	v_add_co_u32_e32 v22, vcc, s4, v100
	global_load_dwordx4 v[2:5], v[98:99], off
	s_nop 0
	v_addc_co_u32_e32 v23, vcc, 0, v101, vcc
	v_add_co_u32_e32 v26, vcc, s5, v100
	global_load_dwordx4 v[6:9], v[6:7], off
	s_nop 0
	global_load_dwordx4 v[10:13], v[10:11], off
	v_addc_co_u32_e32 v27, vcc, 0, v101, vcc
	global_load_dwordx4 v[14:17], v[14:15], off
	v_add_co_u32_e32 v30, vcc, s8, v100
	global_load_dwordx4 v[18:21], v[100:101], off
	s_nop 0
	global_load_dwordx4 v[22:25], v[22:23], off
	s_nop 0
	global_load_dwordx4 v[26:29], v[26:27], off
	v_addc_co_u32_e32 v31, vcc, 0, v101, vcc
	global_load_dwordx4 v[30:33], v[30:31], off
	v_ashrrev_i32_e32 v37, 4, v1
	s_waitcnt vmcnt(8)
	v_lshrrev_b32_e32 v38, 5, v1
	v_xor_b32_e32 v41, v37, v1
	v_and_b32_e32 v37, 1, v37
	v_and_b32_e32 v38, 6, v38
	v_lshrrev_b32_e32 v36, 4, v1
	v_bfe_u32 v39, v1, 1, 3
	v_bitop3_b32 v35, v37, v35, v38 bitop3:0x36
	v_lshlrev_b32_e32 v105, 7, v34
	v_bitop3_b32 v34, v36, v39, 3 bitop3:0x6c
	v_lshlrev_b32_e32 v37, 4, v41
	s_movk_i32 s4, 0x70
	v_lshlrev_b32_e32 v109, 4, v35
	v_lshlrev_b32_e32 v106, 4, v34
	v_and_or_b32 v108, v37, s4, v105
	v_or_b32_e32 v34, v105, v109
	v_lshlrev_b32_e32 v40, 1, v1
	v_bfe_u32 v102, v1, 4, 2
	v_ashrrev_i32_e32 v103, 7, v1
	v_and_b32_e32 v104, 15, v1
	v_lshlrev_b32_e32 v36, 13, v103
	v_lshlrev_b32_e32 v42, 7, v104
	v_or_b32_e32 v35, v106, v36
	s_mov_b64 s[10:11], 0
	v_add_u32_e32 v112, v35, v42
	s_waitcnt vmcnt(7)
	ds_write_b128 v108, v[2:5]
	s_waitcnt vmcnt(6)
	ds_write_b128 v108, v[6:9] offset:4096
	s_waitcnt vmcnt(5)
	ds_write_b128 v108, v[10:13] offset:8192
	s_waitcnt vmcnt(4)
	ds_write_b128 v108, v[14:17] offset:12288
	s_waitcnt vmcnt(3)
	ds_write_b128 v34, v[18:21] offset:16384
	s_waitcnt vmcnt(2)
	ds_write_b128 v34, v[22:25] offset:20480
	s_waitcnt vmcnt(1)
	ds_write_b128 v34, v[26:29] offset:24576
	s_waitcnt vmcnt(0)
	ds_write_b128 v34, v[30:33] offset:28672
	v_and_b32_e32 v34, 0x43, v1
	v_and_or_b32 v34, v40, 24, v34
	v_lshlrev_b32_e32 v110, 7, v34
	v_bitop3_b32 v34, v102, v39, 4 bitop3:0x36
	v_lshlrev_b32_e32 v111, 4, v34
	v_or_b32_e32 v36, v111, v36
	v_mov_b32_e32 v34, 0
	v_add_u32_e32 v113, v36, v42
	v_mov_b32_e32 v35, v34
	v_mov_b32_e32 v36, v34
	v_mov_b32_e32 v37, v34
	v_mov_b32_e32 v38, v34
	v_mov_b32_e32 v39, v34
	v_mov_b32_e32 v40, v34
	v_mov_b32_e32 v41, v34
	v_mov_b32_e32 v42, v34
	v_mov_b32_e32 v43, v34
	v_mov_b32_e32 v44, v34
	v_mov_b32_e32 v45, v34
	v_mov_b32_e32 v46, v34
	v_mov_b32_e32 v47, v34
	v_mov_b32_e32 v48, v34
	v_mov_b32_e32 v49, v34
	v_mov_b32_e32 v50, v34
	v_mov_b32_e32 v51, v34
	v_mov_b32_e32 v52, v34
	v_mov_b32_e32 v53, v34
	v_mov_b32_e32 v54, v34
	v_mov_b32_e32 v55, v34
	v_mov_b32_e32 v56, v34
	v_mov_b32_e32 v57, v34
	v_mov_b32_e32 v58, v34
	v_mov_b32_e32 v59, v34
	v_mov_b32_e32 v60, v34
	v_mov_b32_e32 v61, v34
	v_mov_b32_e32 v62, v34
	v_mov_b32_e32 v63, v34
	v_mov_b32_e32 v64, v34
	v_mov_b32_e32 v65, v34
	v_mov_b32_e32 v66, v34
	v_mov_b32_e32 v67, v34
	v_mov_b32_e32 v68, v34
	v_mov_b32_e32 v69, v34
	v_mov_b32_e32 v70, v34
	v_mov_b32_e32 v71, v34
	v_mov_b32_e32 v72, v34
	v_mov_b32_e32 v73, v34
	v_mov_b32_e32 v74, v34
	v_mov_b32_e32 v75, v34
	v_mov_b32_e32 v76, v34
	v_mov_b32_e32 v77, v34
	v_mov_b32_e32 v78, v34
	v_mov_b32_e32 v79, v34
	v_mov_b32_e32 v80, v34
	v_mov_b32_e32 v81, v34
	v_mov_b32_e32 v82, v34
	v_mov_b32_e32 v83, v34
	v_mov_b32_e32 v84, v34
	v_mov_b32_e32 v85, v34
	v_mov_b32_e32 v86, v34
	v_mov_b32_e32 v87, v34
	v_mov_b32_e32 v88, v34
	v_mov_b32_e32 v89, v34
	v_mov_b32_e32 v90, v34
	v_mov_b32_e32 v91, v34
	v_mov_b32_e32 v92, v34
	v_mov_b32_e32 v93, v34
	v_mov_b32_e32 v94, v34
	v_mov_b32_e32 v95, v34
	v_mov_b32_e32 v96, v34
	v_mov_b32_e32 v97, v34
	v_lshl_add_u64 v[224:225], v[98:99], 0, s[10:11]
	global_load_dwordx4 v[224:227], v[224:225], off offset:128
	s_add_u32 s28, s10, 0x11000
	s_addc_u32 s29, s11, 0
	v_lshl_add_u64 v[228:229], v[98:99], 0, s[28:29]
	global_load_dwordx4 v[228:231], v[228:229], off offset:128
	s_add_u32 vcc_lo, s10, 0x22000
	s_addc_u32 vcc_hi, s11, 0
	v_lshl_add_u64 v[232:233], v[98:99], 0, vcc
	global_load_dwordx4 v[232:235], v[232:233], off offset:128
	s_add_u32 s28, s10, 0x33000
	s_addc_u32 s29, s11, 0
	v_lshl_add_u64 v[236:237], v[98:99], 0, s[28:29]
	global_load_dwordx4 v[236:239], v[236:237], off offset:128
	v_lshl_add_u64 v[240:241], v[100:101], 0, s[10:11]
	global_load_dwordx4 v[240:243], v[240:241], off offset:128
	s_add_u32 vcc_lo, s10, 0x11000
	s_addc_u32 vcc_hi, s11, 0
	v_lshl_add_u64 v[244:245], v[100:101], 0, vcc
	global_load_dwordx4 v[244:247], v[244:245], off offset:128
	s_add_u32 s28, s10, 0x22000
	s_addc_u32 s29, s11, 0
	v_lshl_add_u64 v[248:249], v[100:101], 0, s[28:29]
	global_load_dwordx4 v[248:251], v[248:249], off offset:128
	s_add_u32 vcc_lo, s10, 0x33000
	s_addc_u32 vcc_hi, s11, 0
	v_lshl_add_u64 v[252:253], v[100:101], 0, vcc
	global_load_dwordx4 v[252:255], v[252:253], off offset:128
	v_add_u32_e32 v188, v106, v110
	v_add_u32_e32 v189, v111, v110
	v_add_u32_e32 v190, v105, v109
	s_waitcnt lgkmcnt(0)
	s_barrier
	s_branch .LBB0_1386
.LBB0_1386:
.Lgq_o:
	ds_read_b128 v[114:117], v188 offset:16384
	ds_read_b128 v[122:125], v188 offset:16896
	ds_read_b128 v[126:129], v188 offset:20480
	ds_read_b128 v[156:159], v188 offset:20992
	ds_read_b128 v[118:121], v112
	ds_read_b128 v[160:163], v112 offset:2048
	v_lshl_add_u64 v[2:3], v[98:99], 0, s[10:11]
	global_load_dwordx4 v[2:5], v[2:3], off offset:256
	s_add_u32 s28, s10, 0x11000
	s_addc_u32 s29, s11, 0
	v_lshl_add_u64 v[6:7], v[98:99], 0, s[28:29]
	global_load_dwordx4 v[6:9], v[6:7], off offset:256
	s_waitcnt lgkmcnt(1)
	v_mfma_f32_16x16x32_bf16 v[94:97], v[114:117], v[118:121], v[94:97]
	v_mfma_f32_16x16x32_bf16 v[90:93], v[122:125], v[118:121], v[90:93]
	s_add_u32 vcc_lo, s10, 0x22000
	s_addc_u32 vcc_hi, s11, 0
	v_lshl_add_u64 v[10:11], v[98:99], 0, vcc
	global_load_dwordx4 v[10:13], v[10:11], off offset:256
	v_mfma_f32_16x16x32_bf16 v[86:89], v[126:129], v[118:121], v[86:89]
	v_mfma_f32_16x16x32_bf16 v[82:85], v[156:159], v[118:121], v[82:85]
	s_waitcnt lgkmcnt(0)
	v_mfma_f32_16x16x32_bf16 v[78:81], v[114:117], v[160:163], v[78:81]
	ds_read_b128 v[180:183], v112 offset:4096
	ds_read_b128 v[184:187], v112 offset:6144
	v_mfma_f32_16x16x32_bf16 v[74:77], v[122:125], v[160:163], v[74:77]
	v_mfma_f32_16x16x32_bf16 v[70:73], v[126:129], v[160:163], v[70:73]
	s_add_u32 s28, s10, 0x33000
	s_addc_u32 s29, s11, 0
	v_lshl_add_u64 v[14:15], v[98:99], 0, s[28:29]
	global_load_dwordx4 v[14:17], v[14:15], off offset:256
	v_mfma_f32_16x16x32_bf16 v[66:69], v[156:159], v[160:163], v[66:69]
	s_waitcnt lgkmcnt(1)
	v_mfma_f32_16x16x32_bf16 v[62:65], v[114:117], v[180:183], v[62:65]
	ds_read_b128 v[164:167], v189 offset:16384
	ds_read_b128 v[168:171], v189 offset:16896
	v_mfma_f32_16x16x32_bf16 v[58:61], v[122:125], v[180:183], v[58:61]
	v_lshl_add_u64 v[18:19], v[100:101], 0, s[10:11]
	global_load_dwordx4 v[18:21], v[18:19], off offset:256
	v_mfma_f32_16x16x32_bf16 v[54:57], v[126:129], v[180:183], v[54:57]
	ds_read_b128 v[172:175], v189 offset:20480
	ds_read_b128 v[176:179], v189 offset:20992
	v_mfma_f32_16x16x32_bf16 v[50:53], v[156:159], v[180:183], v[50:53]
	s_waitcnt lgkmcnt(4)
	v_mfma_f32_16x16x32_bf16 v[46:49], v[114:117], v[184:187], v[46:49]
	ds_read_b128 v[118:121], v113
	ds_read_b128 v[160:163], v113 offset:2048
	v_mfma_f32_16x16x32_bf16 v[42:45], v[122:125], v[184:187], v[42:45]
	v_mfma_f32_16x16x32_bf16 v[38:41], v[126:129], v[184:187], v[38:41]
	s_add_u32 vcc_lo, s10, 0x11000
	s_addc_u32 vcc_hi, s11, 0
	v_lshl_add_u64 v[22:23], v[100:101], 0, vcc
	global_load_dwordx4 v[22:25], v[22:23], off offset:256
	v_mfma_f32_16x16x32_bf16 v[34:37], v[156:159], v[184:187], v[34:37]
	s_waitcnt lgkmcnt(1)
	v_mfma_f32_16x16x32_bf16 v[94:97], v[164:167], v[118:121], v[94:97]
	v_mfma_f32_16x16x32_bf16 v[90:93], v[168:171], v[118:121], v[90:93]
	s_add_u32 s28, s10, 0x22000
	s_addc_u32 s29, s11, 0
	v_lshl_add_u64 v[26:27], v[100:101], 0, s[28:29]
	global_load_dwordx4 v[26:29], v[26:27], off offset:256
	v_mfma_f32_16x16x32_bf16 v[86:89], v[172:175], v[118:121], v[86:89]
	v_mfma_f32_16x16x32_bf16 v[82:85], v[176:179], v[118:121], v[82:85]
	s_waitcnt lgkmcnt(0)
	v_mfma_f32_16x16x32_bf16 v[78:81], v[164:167], v[160:163], v[78:81]
	ds_read_b128 v[180:183], v113 offset:4096
	ds_read_b128 v[184:187], v113 offset:6144
	v_mfma_f32_16x16x32_bf16 v[74:77], v[168:171], v[160:163], v[74:77]
	v_mfma_f32_16x16x32_bf16 v[70:73], v[172:175], v[160:163], v[70:73]
	s_add_u32 vcc_lo, s10, 0x33000
	s_addc_u32 vcc_hi, s11, 0
	v_lshl_add_u64 v[30:31], v[100:101], 0, vcc
	global_load_dwordx4 v[30:33], v[30:31], off offset:256
	v_mfma_f32_16x16x32_bf16 v[66:69], v[176:179], v[160:163], v[66:69]
	s_waitcnt lgkmcnt(1)
	v_mfma_f32_16x16x32_bf16 v[62:65], v[164:167], v[180:183], v[62:65]
	s_waitcnt vmcnt(15)
	ds_write_b128 v108, v[224:227] offset:32768
	v_mfma_f32_16x16x32_bf16 v[58:61], v[168:171], v[180:183], v[58:61]
	s_waitcnt vmcnt(14)
	ds_write_b128 v108, v[228:231] offset:36864
	v_mfma_f32_16x16x32_bf16 v[54:57], v[172:175], v[180:183], v[54:57]
	s_waitcnt vmcnt(13)
	ds_write_b128 v108, v[232:235] offset:40960
	v_mfma_f32_16x16x32_bf16 v[50:53], v[176:179], v[180:183], v[50:53]
	s_waitcnt vmcnt(12)
	ds_write_b128 v108, v[236:239] offset:45056
	s_waitcnt lgkmcnt(4)
	v_mfma_f32_16x16x32_bf16 v[46:49], v[164:167], v[184:187], v[46:49]
	s_waitcnt vmcnt(11)
	ds_write_b128 v190, v[240:243] offset:49168
	v_mfma_f32_16x16x32_bf16 v[42:45], v[168:171], v[184:187], v[42:45]
	s_waitcnt vmcnt(10)
	ds_write_b128 v190, v[244:247] offset:53264
	v_mfma_f32_16x16x32_bf16 v[38:41], v[172:175], v[184:187], v[38:41]
	s_waitcnt vmcnt(9)
	ds_write_b128 v190, v[248:251] offset:57360
	v_mfma_f32_16x16x32_bf16 v[34:37], v[176:179], v[184:187], v[34:37]
	s_waitcnt vmcnt(8)
	ds_write_b128 v190, v[252:255] offset:61456
	s_waitcnt lgkmcnt(0)
	s_barrier
	s_add_u32 s10, s10, 0x80
	s_addc_u32 s11, s11, 0
	ds_read_b128 v[114:117], v188 offset:49168
	ds_read_b128 v[122:125], v188 offset:49680
	ds_read_b128 v[126:129], v188 offset:53264
	ds_read_b128 v[156:159], v188 offset:53776
	ds_read_b128 v[118:121], v112 offset:32768
	ds_read_b128 v[160:163], v112 offset:34816
	v_lshl_add_u64 v[224:225], v[98:99], 0, s[10:11]
	global_load_dwordx4 v[224:227], v[224:225], off offset:256
	s_add_u32 s28, s10, 0x11000
	s_addc_u32 s29, s11, 0
	v_lshl_add_u64 v[228:229], v[98:99], 0, s[28:29]
	global_load_dwordx4 v[228:231], v[228:229], off offset:256
	s_waitcnt lgkmcnt(1)
	v_mfma_f32_16x16x32_bf16 v[94:97], v[114:117], v[118:121], v[94:97]
	v_mfma_f32_16x16x32_bf16 v[90:93], v[122:125], v[118:121], v[90:93]
	s_add_u32 vcc_lo, s10, 0x22000
	s_addc_u32 vcc_hi, s11, 0
	v_lshl_add_u64 v[232:233], v[98:99], 0, vcc
	global_load_dwordx4 v[232:235], v[232:233], off offset:256
	v_mfma_f32_16x16x32_bf16 v[86:89], v[126:129], v[118:121], v[86:89]
	v_mfma_f32_16x16x32_bf16 v[82:85], v[156:159], v[118:121], v[82:85]
	s_waitcnt lgkmcnt(0)
	v_mfma_f32_16x16x32_bf16 v[78:81], v[114:117], v[160:163], v[78:81]
	ds_read_b128 v[180:183], v112 offset:36864
	ds_read_b128 v[184:187], v112 offset:38912
	v_mfma_f32_16x16x32_bf16 v[74:77], v[122:125], v[160:163], v[74:77]
	v_mfma_f32_16x16x32_bf16 v[70:73], v[126:129], v[160:163], v[70:73]
	s_add_u32 s28, s10, 0x33000
	s_addc_u32 s29, s11, 0
	v_lshl_add_u64 v[236:237], v[98:99], 0, s[28:29]
	global_load_dwordx4 v[236:239], v[236:237], off offset:256
	v_mfma_f32_16x16x32_bf16 v[66:69], v[156:159], v[160:163], v[66:69]
	s_waitcnt lgkmcnt(1)
	v_mfma_f32_16x16x32_bf16 v[62:65], v[114:117], v[180:183], v[62:65]
	ds_read_b128 v[164:167], v189 offset:49168
	ds_read_b128 v[168:171], v189 offset:49680
	v_mfma_f32_16x16x32_bf16 v[58:61], v[122:125], v[180:183], v[58:61]
	v_lshl_add_u64 v[240:241], v[100:101], 0, s[10:11]
	global_load_dwordx4 v[240:243], v[240:241], off offset:256
	v_mfma_f32_16x16x32_bf16 v[54:57], v[126:129], v[180:183], v[54:57]
	ds_read_b128 v[172:175], v189 offset:53264
	ds_read_b128 v[176:179], v189 offset:53776
	v_mfma_f32_16x16x32_bf16 v[50:53], v[156:159], v[180:183], v[50:53]
	s_waitcnt lgkmcnt(4)
	v_mfma_f32_16x16x32_bf16 v[46:49], v[114:117], v[184:187], v[46:49]
	ds_read_b128 v[118:121], v113 offset:32768
	ds_read_b128 v[160:163], v113 offset:34816
	v_mfma_f32_16x16x32_bf16 v[42:45], v[122:125], v[184:187], v[42:45]
	v_mfma_f32_16x16x32_bf16 v[38:41], v[126:129], v[184:187], v[38:41]
	s_add_u32 vcc_lo, s10, 0x11000
	s_addc_u32 vcc_hi, s11, 0
	v_lshl_add_u64 v[244:245], v[100:101], 0, vcc
	global_load_dwordx4 v[244:247], v[244:245], off offset:256
	v_mfma_f32_16x16x32_bf16 v[34:37], v[156:159], v[184:187], v[34:37]
	s_waitcnt lgkmcnt(1)
	v_mfma_f32_16x16x32_bf16 v[94:97], v[164:167], v[118:121], v[94:97]
	v_mfma_f32_16x16x32_bf16 v[90:93], v[168:171], v[118:121], v[90:93]
	s_add_u32 s28, s10, 0x22000
	s_addc_u32 s29, s11, 0
	v_lshl_add_u64 v[248:249], v[100:101], 0, s[28:29]
	global_load_dwordx4 v[248:251], v[248:249], off offset:256
	v_mfma_f32_16x16x32_bf16 v[86:89], v[172:175], v[118:121], v[86:89]
	v_mfma_f32_16x16x32_bf16 v[82:85], v[176:179], v[118:121], v[82:85]
	s_waitcnt lgkmcnt(0)
	v_mfma_f32_16x16x32_bf16 v[78:81], v[164:167], v[160:163], v[78:81]
	ds_read_b128 v[180:183], v113 offset:36864
	ds_read_b128 v[184:187], v113 offset:38912
	v_mfma_f32_16x16x32_bf16 v[74:77], v[168:171], v[160:163], v[74:77]
	v_mfma_f32_16x16x32_bf16 v[70:73], v[172:175], v[160:163], v[70:73]
	s_add_u32 vcc_lo, s10, 0x33000
	s_addc_u32 vcc_hi, s11, 0
	v_lshl_add_u64 v[252:253], v[100:101], 0, vcc
	global_load_dwordx4 v[252:255], v[252:253], off offset:256
	v_mfma_f32_16x16x32_bf16 v[66:69], v[176:179], v[160:163], v[66:69]
	s_waitcnt lgkmcnt(1)
	v_mfma_f32_16x16x32_bf16 v[62:65], v[164:167], v[180:183], v[62:65]
	s_waitcnt vmcnt(15)
	ds_write_b128 v108, v[2:5]
	v_mfma_f32_16x16x32_bf16 v[58:61], v[168:171], v[180:183], v[58:61]
	s_waitcnt vmcnt(14)
	ds_write_b128 v108, v[6:9] offset:4096
	v_mfma_f32_16x16x32_bf16 v[54:57], v[172:175], v[180:183], v[54:57]
	s_waitcnt vmcnt(13)
	ds_write_b128 v108, v[10:13] offset:8192
	v_mfma_f32_16x16x32_bf16 v[50:53], v[176:179], v[180:183], v[50:53]
	s_waitcnt vmcnt(12)
	ds_write_b128 v108, v[14:17] offset:12288
	s_waitcnt lgkmcnt(4)
	v_mfma_f32_16x16x32_bf16 v[46:49], v[164:167], v[184:187], v[46:49]
	s_waitcnt vmcnt(11)
	ds_write_b128 v190, v[18:21] offset:16384
	v_mfma_f32_16x16x32_bf16 v[42:45], v[168:171], v[184:187], v[42:45]
	s_waitcnt vmcnt(10)
	ds_write_b128 v190, v[22:25] offset:20480
	v_mfma_f32_16x16x32_bf16 v[38:41], v[172:175], v[184:187], v[38:41]
	s_waitcnt vmcnt(9)
	ds_write_b128 v190, v[26:29] offset:24576
	v_mfma_f32_16x16x32_bf16 v[34:37], v[176:179], v[184:187], v[34:37]
	s_waitcnt vmcnt(8)
	ds_write_b128 v190, v[30:33] offset:28672
	s_waitcnt lgkmcnt(0)
	s_barrier
	s_add_u32 s10, s10, 0x80
	s_addc_u32 s11, s11, 0
	s_cmpk_lg_i32 s10, 0x700
	s_cbranch_scc1 .Lgq_o
	ds_read_b128 v[114:117], v188 offset:16384
	ds_read_b128 v[122:125], v188 offset:16896
	ds_read_b128 v[126:129], v188 offset:20480
	ds_read_b128 v[156:159], v188 offset:20992
	ds_read_b128 v[118:121], v112
	ds_read_b128 v[160:163], v112 offset:2048
	s_waitcnt lgkmcnt(1)
	v_mfma_f32_16x16x32_bf16 v[94:97], v[114:117], v[118:121], v[94:97]
	v_mfma_f32_16x16x32_bf16 v[90:93], v[122:125], v[118:121], v[90:93]
	v_mfma_f32_16x16x32_bf16 v[86:89], v[126:129], v[118:121], v[86:89]
	v_mfma_f32_16x16x32_bf16 v[82:85], v[156:159], v[118:121], v[82:85]
	s_waitcnt lgkmcnt(0)
	v_mfma_f32_16x16x32_bf16 v[78:81], v[114:117], v[160:163], v[78:81]
	ds_read_b128 v[180:183], v112 offset:4096
	ds_read_b128 v[184:187], v112 offset:6144
	v_mfma_f32_16x16x32_bf16 v[74:77], v[122:125], v[160:163], v[74:77]
	v_mfma_f32_16x16x32_bf16 v[70:73], v[126:129], v[160:163], v[70:73]
	v_mfma_f32_16x16x32_bf16 v[66:69], v[156:159], v[160:163], v[66:69]
	s_waitcnt lgkmcnt(1)
	v_mfma_f32_16x16x32_bf16 v[62:65], v[114:117], v[180:183], v[62:65]
	ds_read_b128 v[164:167], v189 offset:16384
	ds_read_b128 v[168:171], v189 offset:16896
	v_mfma_f32_16x16x32_bf16 v[58:61], v[122:125], v[180:183], v[58:61]
	v_mfma_f32_16x16x32_bf16 v[54:57], v[126:129], v[180:183], v[54:57]
	ds_read_b128 v[172:175], v189 offset:20480
	ds_read_b128 v[176:179], v189 offset:20992
	v_mfma_f32_16x16x32_bf16 v[50:53], v[156:159], v[180:183], v[50:53]
	s_waitcnt lgkmcnt(4)
	v_mfma_f32_16x16x32_bf16 v[46:49], v[114:117], v[184:187], v[46:49]
	ds_read_b128 v[118:121], v113
	ds_read_b128 v[160:163], v113 offset:2048
	v_mfma_f32_16x16x32_bf16 v[42:45], v[122:125], v[184:187], v[42:45]
	v_mfma_f32_16x16x32_bf16 v[38:41], v[126:129], v[184:187], v[38:41]
	v_mfma_f32_16x16x32_bf16 v[34:37], v[156:159], v[184:187], v[34:37]
	s_waitcnt lgkmcnt(1)
	v_mfma_f32_16x16x32_bf16 v[94:97], v[164:167], v[118:121], v[94:97]
	v_mfma_f32_16x16x32_bf16 v[90:93], v[168:171], v[118:121], v[90:93]
	v_mfma_f32_16x16x32_bf16 v[86:89], v[172:175], v[118:121], v[86:89]
	v_mfma_f32_16x16x32_bf16 v[82:85], v[176:179], v[118:121], v[82:85]
	s_waitcnt lgkmcnt(0)
	v_mfma_f32_16x16x32_bf16 v[78:81], v[164:167], v[160:163], v[78:81]
	ds_read_b128 v[180:183], v113 offset:4096
	ds_read_b128 v[184:187], v113 offset:6144
	v_mfma_f32_16x16x32_bf16 v[74:77], v[168:171], v[160:163], v[74:77]
	v_mfma_f32_16x16x32_bf16 v[70:73], v[172:175], v[160:163], v[70:73]
	v_mfma_f32_16x16x32_bf16 v[66:69], v[176:179], v[160:163], v[66:69]
	s_waitcnt lgkmcnt(1)
	v_mfma_f32_16x16x32_bf16 v[62:65], v[164:167], v[180:183], v[62:65]
	s_waitcnt vmcnt(7)
	ds_write_b128 v108, v[224:227] offset:32768
	v_mfma_f32_16x16x32_bf16 v[58:61], v[168:171], v[180:183], v[58:61]
	s_waitcnt vmcnt(6)
	ds_write_b128 v108, v[228:231] offset:36864
	v_mfma_f32_16x16x32_bf16 v[54:57], v[172:175], v[180:183], v[54:57]
	s_waitcnt vmcnt(5)
	ds_write_b128 v108, v[232:235] offset:40960
	v_mfma_f32_16x16x32_bf16 v[50:53], v[176:179], v[180:183], v[50:53]
	s_waitcnt vmcnt(4)
	ds_write_b128 v108, v[236:239] offset:45056
	s_waitcnt lgkmcnt(4)
	v_mfma_f32_16x16x32_bf16 v[46:49], v[164:167], v[184:187], v[46:49]
	s_waitcnt vmcnt(3)
	ds_write_b128 v190, v[240:243] offset:49168
	v_mfma_f32_16x16x32_bf16 v[42:45], v[168:171], v[184:187], v[42:45]
	s_waitcnt vmcnt(2)
	ds_write_b128 v190, v[244:247] offset:53264
	v_mfma_f32_16x16x32_bf16 v[38:41], v[172:175], v[184:187], v[38:41]
	s_waitcnt vmcnt(1)
	ds_write_b128 v190, v[248:251] offset:57360
	v_mfma_f32_16x16x32_bf16 v[34:37], v[176:179], v[184:187], v[34:37]
	s_waitcnt vmcnt(0)
	ds_write_b128 v190, v[252:255] offset:61456
	s_waitcnt lgkmcnt(0)
	s_barrier
	ds_read_b128 v[114:117], v188 offset:49168
	ds_read_b128 v[122:125], v188 offset:49680
	ds_read_b128 v[126:129], v188 offset:53264
	ds_read_b128 v[156:159], v188 offset:53776
	ds_read_b128 v[118:121], v112 offset:32768
	ds_read_b128 v[160:163], v112 offset:34816
	s_waitcnt lgkmcnt(1)
	v_mfma_f32_16x16x32_bf16 v[94:97], v[114:117], v[118:121], v[94:97]
	v_mfma_f32_16x16x32_bf16 v[90:93], v[122:125], v[118:121], v[90:93]
	v_mfma_f32_16x16x32_bf16 v[86:89], v[126:129], v[118:121], v[86:89]
	v_mfma_f32_16x16x32_bf16 v[82:85], v[156:159], v[118:121], v[82:85]
	s_waitcnt lgkmcnt(0)
	v_mfma_f32_16x16x32_bf16 v[78:81], v[114:117], v[160:163], v[78:81]
	ds_read_b128 v[180:183], v112 offset:36864
	ds_read_b128 v[184:187], v112 offset:38912
	v_mfma_f32_16x16x32_bf16 v[74:77], v[122:125], v[160:163], v[74:77]
	v_mfma_f32_16x16x32_bf16 v[70:73], v[126:129], v[160:163], v[70:73]
	v_mfma_f32_16x16x32_bf16 v[66:69], v[156:159], v[160:163], v[66:69]
	s_waitcnt lgkmcnt(1)
	v_mfma_f32_16x16x32_bf16 v[62:65], v[114:117], v[180:183], v[62:65]
	ds_read_b128 v[164:167], v189 offset:49168
	ds_read_b128 v[168:171], v189 offset:49680
	v_mfma_f32_16x16x32_bf16 v[58:61], v[122:125], v[180:183], v[58:61]
	v_mfma_f32_16x16x32_bf16 v[54:57], v[126:129], v[180:183], v[54:57]
	ds_read_b128 v[172:175], v189 offset:53264
	ds_read_b128 v[176:179], v189 offset:53776
	v_mfma_f32_16x16x32_bf16 v[50:53], v[156:159], v[180:183], v[50:53]
	s_waitcnt lgkmcnt(4)
	v_mfma_f32_16x16x32_bf16 v[46:49], v[114:117], v[184:187], v[46:49]
	ds_read_b128 v[118:121], v113 offset:32768
	ds_read_b128 v[160:163], v113 offset:34816
	v_mfma_f32_16x16x32_bf16 v[42:45], v[122:125], v[184:187], v[42:45]
	v_mfma_f32_16x16x32_bf16 v[38:41], v[126:129], v[184:187], v[38:41]
	v_mfma_f32_16x16x32_bf16 v[34:37], v[156:159], v[184:187], v[34:37]
	s_waitcnt lgkmcnt(1)
	v_mfma_f32_16x16x32_bf16 v[94:97], v[164:167], v[118:121], v[94:97]
	v_mfma_f32_16x16x32_bf16 v[90:93], v[168:171], v[118:121], v[90:93]
	v_mfma_f32_16x16x32_bf16 v[86:89], v[172:175], v[118:121], v[86:89]
	v_mfma_f32_16x16x32_bf16 v[82:85], v[176:179], v[118:121], v[82:85]
	s_waitcnt lgkmcnt(0)
	v_mfma_f32_16x16x32_bf16 v[78:81], v[164:167], v[160:163], v[78:81]
	ds_read_b128 v[180:183], v113 offset:36864
	ds_read_b128 v[184:187], v113 offset:38912
	v_mfma_f32_16x16x32_bf16 v[74:77], v[168:171], v[160:163], v[74:77]
	v_mfma_f32_16x16x32_bf16 v[70:73], v[172:175], v[160:163], v[70:73]
	v_mfma_f32_16x16x32_bf16 v[66:69], v[176:179], v[160:163], v[66:69]
	s_waitcnt lgkmcnt(1)
	v_mfma_f32_16x16x32_bf16 v[62:65], v[164:167], v[180:183], v[62:65]
	v_mfma_f32_16x16x32_bf16 v[58:61], v[168:171], v[180:183], v[58:61]
	v_mfma_f32_16x16x32_bf16 v[54:57], v[172:175], v[180:183], v[54:57]
	v_mfma_f32_16x16x32_bf16 v[50:53], v[176:179], v[180:183], v[50:53]
	s_waitcnt lgkmcnt(0)
	v_mfma_f32_16x16x32_bf16 v[46:49], v[164:167], v[184:187], v[46:49]
	v_mfma_f32_16x16x32_bf16 v[42:45], v[168:171], v[184:187], v[42:45]
	v_mfma_f32_16x16x32_bf16 v[38:41], v[172:175], v[184:187], v[38:41]
	v_mfma_f32_16x16x32_bf16 v[34:37], v[176:179], v[184:187], v[34:37]
	s_barrier
	s_branch .LBB0_1383
